# attnA: 46 of 48 relative-position-bias LDS lookups issued together after QK^T instead of one by one
# speedup vs baseline: 1.0047x; 1.0047x over previous
; #define LAS __attribute__((address_space(3)))
; template <int NCT>
; __device__ __forceinline__ void qk_accum(f32x4 (&s)[NCT], const LAS unsigned char* Kt, int key_row0, const bf16x8 (&qf)[4], int fr, int fq) {
; #pragma unroll
;     for (int ct = 0; ct < NCT; ++ct)
; #pragma unroll
;         for (int ks = 0; ks < 4; ++ks) { const bf16x8 kf = *(const LAS bf16x8*)(Kt + (key_row0 + 16 * ct + fr) * AT_PITCH + 64 * ks + 16 * fq);
;             s[ct] = __builtin_amdgcn_mfma_f32_16x16x32_bf16(kf, qf[ks], s[ct], 0, 0, 0); if (ks == 3 && (ct & 1)) asm volatile("" ::: "memory"); }
; }
; __device__ __forceinline__ void attnA_item(const Frame& F, const Args& a, int item) {
;     ...
;     const int qq = 16 * (F.wave & 3) + fr;
;     const int qpos = (n0 + hb) * 64 + qq;
;     const size_t qrow = rowbase + (size_t)qpos * d + r;
;     bf16x8 qf[4];
; #pragma unroll
;     for (int ks = 0; ks < 4; ++ks) qf[ks] = *(const bf16x8*)(proj + qrow * NIN + C_Q + h * 128 + 32 * ks + 8 * fq);
;     __syncthreads();
;     f32x4 s[12];
; #pragma unroll
;     for (int ct = 0; ct < 12; ++ct) s[ct] = (f32x4){0.f, 0.f, 0.f, 0.f};
;     qk_accum<12>(s, R0, 64 * hb, qf, fr, fq);
.LBB0_292:
	s_or_b64 exec, exec, s[72:73]
	s_add_i32 s12, s12, s95
	v_or_b32_e32 v66, s12, v85
	v_lshlrev_b64 v[0:1], s11, v[66:67]
	v_lshl_add_u64 v[60:61], v[0:1], 0, s[8:9]
	v_mov_b64_e32 v[0:1], s[96:97]
	v_mad_u64_u32 v[0:1], s[8:9], v60, s93, v[0:1]
	v_mov_b32_e32 v2, v1
	v_mad_u64_u32 v[2:3], s[8:9], v61, s93, v[2:3]
	v_mov_b32_e32 v1, v2
	v_lshl_add_u64 v[0:1], s[0:1], 1, v[0:1]
	v_mov_b32_e32 v71, v67
	v_lshl_add_u64 v[0:1], v[0:1], 0, v[70:71]
	global_load_dwordx4 v[56:59], v[0:1], off
	global_load_dwordx4 v[52:55], v[0:1], off offset:64
	global_load_dwordx4 v[48:51], v[0:1], off offset:128
	s_nop 0
	global_load_dwordx4 v[0:3], v[0:1], off offset:192
	s_waitcnt lgkmcnt(0)
	s_barrier
	s_sub_i32 s1, s12, 64
	s_cmp_lg_u32 s12, 0
	v_readlane_b32 s14, v242, 44
	s_cselect_b64 s[8:9], -1, 0
	v_readlane_b32 s15, v242, 45
	s_and_b64 s[14:15], s[14:15], s[8:9]
	ds_read_b128 v[208:211], v195
	ds_read_b128 v[212:215], v195 offset:64
	ds_read_b128 v[216:219], v195 offset:128
	ds_read_b128 v[220:223], v195 offset:192
	ds_read_b128 v[224:227], v195 offset:4352
	ds_read_b128 v[228:231], v195 offset:4416
	ds_read_b128 v[232:235], v195 offset:4480
	ds_read_b128 v[236:239], v195 offset:4544
	ds_read_b128 v[244:247], v195 offset:8704
	ds_read_b128 v[248:251], v195 offset:8768
	ds_read_b128 v[252:255], v195 offset:8832
	s_waitcnt vmcnt(0)
	s_waitcnt lgkmcnt(10)
	v_mfma_f32_16x16x32_bf16 v[4:7], v[208:211], v[56:59], 0
	ds_read_b128 v[208:211], v195 offset:8896
	s_waitcnt lgkmcnt(10)
	v_mfma_f32_16x16x32_bf16 v[4:7], v[212:215], v[52:55], v[4:7]
	ds_read_b128 v[212:215], v195 offset:13056
	s_waitcnt lgkmcnt(10)
	v_mfma_f32_16x16x32_bf16 v[4:7], v[216:219], v[48:51], v[4:7]
	ds_read_b128 v[216:219], v195 offset:13120
	s_waitcnt lgkmcnt(10)
	v_mfma_f32_16x16x32_bf16 v[44:47], v[220:223], v[0:3], v[4:7]
	ds_read_b128 v[220:223], v195 offset:13184
	s_waitcnt lgkmcnt(10)
	v_mfma_f32_16x16x32_bf16 v[4:7], v[224:227], v[56:59], 0
	ds_read_b128 v[224:227], v195 offset:13248
	s_waitcnt lgkmcnt(10)
	v_mfma_f32_16x16x32_bf16 v[4:7], v[228:231], v[52:55], v[4:7]
	ds_read_b128 v[228:231], v195 offset:17408
	s_waitcnt lgkmcnt(10)
	v_mfma_f32_16x16x32_bf16 v[4:7], v[232:235], v[48:51], v[4:7]
	ds_read_b128 v[232:235], v195 offset:17472
	s_waitcnt lgkmcnt(10)
	v_mfma_f32_16x16x32_bf16 v[40:43], v[236:239], v[0:3], v[4:7]
	ds_read_b128 v[236:239], v195 offset:17536
	s_waitcnt lgkmcnt(10)
	v_mfma_f32_16x16x32_bf16 v[4:7], v[244:247], v[56:59], 0
	ds_read_b128 v[244:247], v195 offset:17600
	s_waitcnt lgkmcnt(10)
	v_mfma_f32_16x16x32_bf16 v[4:7], v[248:251], v[52:55], v[4:7]
	ds_read_b128 v[248:251], v195 offset:21760
	s_waitcnt lgkmcnt(10)
	v_mfma_f32_16x16x32_bf16 v[4:7], v[252:255], v[48:51], v[4:7]
	ds_read_b128 v[252:255], v195 offset:21824
	s_waitcnt lgkmcnt(10)
	v_mfma_f32_16x16x32_bf16 v[36:39], v[208:211], v[0:3], v[4:7]
	ds_read_b128 v[208:211], v195 offset:21888
	s_waitcnt lgkmcnt(10)
	v_mfma_f32_16x16x32_bf16 v[4:7], v[212:215], v[56:59], 0
	ds_read_b128 v[212:215], v195 offset:21952
	s_waitcnt lgkmcnt(10)
	v_mfma_f32_16x16x32_bf16 v[4:7], v[216:219], v[52:55], v[4:7]
	ds_read_b128 v[216:219], v195 offset:26112
	s_waitcnt lgkmcnt(10)
	v_mfma_f32_16x16x32_bf16 v[4:7], v[220:223], v[48:51], v[4:7]
	ds_read_b128 v[220:223], v195 offset:26176
	s_waitcnt lgkmcnt(10)
	v_mfma_f32_16x16x32_bf16 v[32:35], v[224:227], v[0:3], v[4:7]
	ds_read_b128 v[224:227], v195 offset:26240
	s_waitcnt lgkmcnt(10)
	v_mfma_f32_16x16x32_bf16 v[4:7], v[228:231], v[56:59], 0
	ds_read_b128 v[228:231], v195 offset:26304
	s_waitcnt lgkmcnt(10)
	v_mfma_f32_16x16x32_bf16 v[4:7], v[232:235], v[52:55], v[4:7]
	ds_read_b128 v[232:235], v195 offset:30464
	s_waitcnt lgkmcnt(10)
	v_mfma_f32_16x16x32_bf16 v[4:7], v[236:239], v[48:51], v[4:7]
	ds_read_b128 v[236:239], v195 offset:30528
	s_waitcnt lgkmcnt(10)
	v_mfma_f32_16x16x32_bf16 v[20:23], v[244:247], v[0:3], v[4:7]
	ds_read_b128 v[244:247], v195 offset:30592
	s_waitcnt lgkmcnt(10)
	v_mfma_f32_16x16x32_bf16 v[4:7], v[248:251], v[56:59], 0
	ds_read_b128 v[248:251], v195 offset:30656
	s_waitcnt lgkmcnt(10)
	v_mfma_f32_16x16x32_bf16 v[4:7], v[252:255], v[52:55], v[4:7]
	ds_read_b128 v[252:255], v195 offset:34816
	s_waitcnt lgkmcnt(10)
	v_mfma_f32_16x16x32_bf16 v[4:7], v[208:211], v[48:51], v[4:7]
	ds_read_b128 v[208:211], v195 offset:34880
	s_waitcnt lgkmcnt(10)
	v_mfma_f32_16x16x32_bf16 v[16:19], v[212:215], v[0:3], v[4:7]
	ds_read_b128 v[212:215], v195 offset:34944
	s_waitcnt lgkmcnt(10)
	v_mfma_f32_16x16x32_bf16 v[4:7], v[216:219], v[56:59], 0
	ds_read_b128 v[216:219], v195 offset:35008
	s_waitcnt lgkmcnt(10)
	v_mfma_f32_16x16x32_bf16 v[4:7], v[220:223], v[52:55], v[4:7]
	ds_read_b128 v[220:223], v195 offset:39168
	s_waitcnt lgkmcnt(10)
	v_mfma_f32_16x16x32_bf16 v[4:7], v[224:227], v[48:51], v[4:7]
	ds_read_b128 v[224:227], v195 offset:39232
	s_waitcnt lgkmcnt(10)
	v_mfma_f32_16x16x32_bf16 v[28:31], v[228:231], v[0:3], v[4:7]
	ds_read_b128 v[228:231], v195 offset:39296
	s_waitcnt lgkmcnt(10)
	v_mfma_f32_16x16x32_bf16 v[4:7], v[232:235], v[56:59], 0
	ds_read_b128 v[232:235], v195 offset:39360
	s_waitcnt lgkmcnt(10)
	v_mfma_f32_16x16x32_bf16 v[4:7], v[236:239], v[52:55], v[4:7]
	ds_read_b128 v[236:239], v195 offset:43584
	s_waitcnt lgkmcnt(10)
	v_mfma_f32_16x16x32_bf16 v[4:7], v[244:247], v[48:51], v[4:7]
	ds_read_b128 v[244:247], v195 offset:43520
	s_waitcnt lgkmcnt(10)
	v_mfma_f32_16x16x32_bf16 v[24:27], v[248:251], v[0:3], v[4:7]
	ds_read_b128 v[248:251], v195 offset:43648
	s_waitcnt lgkmcnt(10)
	v_mfma_f32_16x16x32_bf16 v[4:7], v[252:255], v[56:59], 0
	ds_read_b128 v[252:255], v195 offset:43712
	s_waitcnt lgkmcnt(10)
; __device__ __forceinline__ void attnA_item(const Frame& F, const Args& a, int item) {
;     ...
;     for (int ct = 0; ct < 12; ++ct)
; #pragma unroll
;         for (int j = 0; j < 4; ++j) { const int kk = 16 * ct + 4 * fq + j; const int rel = kk - 64 - qq; const int kp = kpw + kk;
;             const bool valid = (rel >= -64) && (rel <= 64) && (kp >= 0) && (kp < L);
;             const float bias = tab[valid ? rel + 64 : 64];
;             const float l = valid ? s[ct][j] * scale + bias : -1e30f; s[ct][j] = l; mx = fmaxf(mx, l); }
	v_mfma_f32_16x16x32_bf16 v[4:7], v[208:211], v[52:55], v[4:7]
	ds_read_b128 v[208:211], v195 offset:47872
	s_waitcnt lgkmcnt(10)
	v_mfma_f32_16x16x32_bf16 v[4:7], v[212:215], v[48:51], v[4:7]
	ds_read_b128 v[212:215], v195 offset:47936
	s_waitcnt lgkmcnt(10)
	v_mfma_f32_16x16x32_bf16 v[12:15], v[216:219], v[0:3], v[4:7]
	ds_read_b128 v[216:219], v195 offset:48000
	s_waitcnt lgkmcnt(10)
	v_mfma_f32_16x16x32_bf16 v[4:7], v[220:223], v[56:59], 0
	ds_read_b128 v[220:223], v195 offset:48064
	s_waitcnt lgkmcnt(10)
	v_mfma_f32_16x16x32_bf16 v[4:7], v[224:227], v[52:55], v[4:7]
	s_waitcnt lgkmcnt(9)
	v_mfma_f32_16x16x32_bf16 v[4:7], v[228:231], v[48:51], v[4:7]
	s_waitcnt lgkmcnt(8)
	v_mfma_f32_16x16x32_bf16 v[8:11], v[232:235], v[0:3], v[4:7]
	s_waitcnt lgkmcnt(6)
	v_mfma_f32_16x16x32_bf16 v[4:7], v[244:247], v[56:59], 0
	s_waitcnt lgkmcnt(7)
	v_mfma_f32_16x16x32_bf16 v[4:7], v[236:239], v[52:55], v[4:7]
	s_waitcnt lgkmcnt(5)
	v_mfma_f32_16x16x32_bf16 v[4:7], v[248:251], v[48:51], v[4:7]
	s_waitcnt lgkmcnt(4)
	v_mfma_f32_16x16x32_bf16 v[4:7], v[252:255], v[0:3], v[4:7]
	s_waitcnt lgkmcnt(3)
	v_mfma_f32_16x16x32_bf16 v[56:59], v[208:211], v[56:59], 0
	s_waitcnt lgkmcnt(2)
	v_mfma_f32_16x16x32_bf16 v[52:55], v[212:215], v[52:55], v[56:59]
	s_waitcnt lgkmcnt(1)
	v_mfma_f32_16x16x32_bf16 v[48:51], v[216:219], v[48:51], v[52:55]
	s_waitcnt lgkmcnt(0)
	v_mfma_f32_16x16x32_bf16 v[0:3], v[220:223], v[0:3], v[48:51]
	s_nop 2
	ds_read_b32 v208, v86
	ds_read_b32 v209, v88
	ds_read_b32 v210, v90
	ds_read_b32 v211, v92
	ds_read_b32 v212, v94
	ds_read_b32 v213, v96
	ds_read_b32 v214, v98
	ds_read_b32 v215, v100
	ds_read_b32 v216, v102
	ds_read_b32 v217, v104
	ds_read_b32 v218, v106
	ds_read_b32 v219, v108
	ds_read_b32 v220, v110
	ds_read_b32 v221, v112
	ds_read_b32 v222, v114
	ds_read_b32 v223, v116
	ds_read_b32 v224, v117
	ds_read_b32 v225, v119
	ds_read_b32 v226, v121
	ds_read_b32 v227, v123
	ds_read_b32 v228, v125
	ds_read_b32 v229, v127
	ds_read_b32 v230, v129
	ds_read_b32 v231, v131
	ds_read_b32 v232, v133
	ds_read_b32 v233, v135
	ds_read_b32 v234, v137
	ds_read_b32 v235, v139
	ds_read_b32 v236, v141
	ds_read_b32 v237, v143
	ds_read_b32 v238, v146
	ds_read_b32 v239, v148
	ds_read_b32 v240, v150
	ds_read_b32 v241, v152
	ds_read_b32 v244, v154
	ds_read_b32 v245, v156
	ds_read_b32 v246, v158
	ds_read_b32 v247, v160
	ds_read_b32 v248, v162
	ds_read_b32 v249, v164
	ds_read_b32 v250, v166
	ds_read_b32 v251, v168
	ds_read_b32 v252, v170
	ds_read_b32 v253, v172
	ds_read_b32 v254, v174
	ds_read_b32 v255, v176
	s_waitcnt lgkmcnt(0)
	v_or_b32_e32 v48, s1, v68
	v_cmp_gt_i32_e32 vcc, s10, v48
	s_and_b64 s[14:15], s[14:15], vcc
	v_mov_b32_e32 v48, 0xf149f2ca
	v_mov_b32_e32 v49, 0xf149f2ca
	s_and_saveexec_b64 s[72:73], s[14:15]
	s_cbranch_execz .LBB0_294
	v_mov_b32_e32 v49, v208
	v_fmac_f32_e32 v49, 0x3db504f3, v44
.LBB0_294:
	s_or_b64 exec, exec, s[72:73]
	v_readlane_b32 s14, v242, 46
	v_or_b32_e32 v44, s1, v87
	v_readlane_b32 s15, v242, 47
	s_and_b64 s[14:15], s[14:15], s[8:9]
	v_cmp_gt_i32_e32 vcc, s10, v44
	s_and_b64 s[14:15], s[14:15], vcc
	s_and_saveexec_b64 s[72:73], s[14:15]
	s_cbranch_execz .LBB0_296
	v_mov_b32_e32 v48, v209
	v_fmac_f32_e32 v48, 0x3db504f3, v45
.LBB0_296:
	s_or_b64 exec, exec, s[72:73]
	v_readlane_b32 s14, v242, 48
	v_or_b32_e32 v44, s1, v89
	v_readlane_b32 s15, v242, 49
	s_and_b64 s[14:15], s[14:15], s[8:9]
	v_cmp_gt_i32_e32 vcc, s10, v44
	s_and_b64 s[14:15], s[14:15], vcc
	v_mov_b32_e32 v44, 0xf149f2ca
	v_mov_b32_e32 v45, 0xf149f2ca
	s_and_saveexec_b64 s[72:73], s[14:15]
	s_cbranch_execz .LBB0_298
	v_mov_b32_e32 v45, v210
	v_fmac_f32_e32 v45, 0x3db504f3, v46
.LBB0_298:
	s_or_b64 exec, exec, s[72:73]
	v_readlane_b32 s14, v242, 50
	v_or_b32_e32 v46, s1, v91
	v_readlane_b32 s15, v242, 51
	s_and_b64 s[14:15], s[14:15], s[8:9]
	v_cmp_gt_i32_e32 vcc, s10, v46
	s_and_b64 s[14:15], s[14:15], vcc
	s_and_saveexec_b64 s[72:73], s[14:15]
	s_cbranch_execz .LBB0_300
	v_mov_b32_e32 v44, v211
	v_fmac_f32_e32 v44, 0x3db504f3, v47
.LBB0_300:
	s_or_b64 exec, exec, s[72:73]
	v_readlane_b32 s14, v242, 52
	v_or_b32_e32 v46, s1, v93
	v_readlane_b32 s15, v242, 53
	s_and_b64 s[14:15], s[14:15], s[8:9]
	v_cmp_gt_i32_e32 vcc, s10, v46
	s_and_b64 s[14:15], s[14:15], vcc
	v_mov_b32_e32 v46, 0xf149f2ca
	v_mov_b32_e32 v47, 0xf149f2ca
	s_and_saveexec_b64 s[72:73], s[14:15]
	s_cbranch_execz .LBB0_302
	v_mov_b32_e32 v47, v212
	v_fmac_f32_e32 v47, 0x3db504f3, v40
.LBB0_302:
	s_or_b64 exec, exec, s[72:73]
	v_readlane_b32 s14, v242, 54
	v_or_b32_e32 v40, s1, v95
	v_readlane_b32 s15, v242, 55
	s_and_b64 s[14:15], s[14:15], s[8:9]
	v_cmp_gt_i32_e32 vcc, s10, v40
	s_and_b64 s[14:15], s[14:15], vcc
	s_and_saveexec_b64 s[72:73], s[14:15]
	s_cbranch_execz .LBB0_304
	v_mov_b32_e32 v46, v213
	v_fmac_f32_e32 v46, 0x3db504f3, v41
.LBB0_304:
	s_or_b64 exec, exec, s[72:73]
	v_readlane_b32 s14, v242, 56
	v_or_b32_e32 v40, s1, v97
	v_readlane_b32 s15, v242, 57
	s_and_b64 s[14:15], s[14:15], s[8:9]
	v_cmp_gt_i32_e32 vcc, s10, v40
	s_and_b64 s[14:15], s[14:15], vcc
	v_mov_b32_e32 v40, 0xf149f2ca
	v_mov_b32_e32 v41, 0xf149f2ca
	s_and_saveexec_b64 s[72:73], s[14:15]
	s_cbranch_execz .LBB0_306
	v_mov_b32_e32 v41, v214
	v_fmac_f32_e32 v41, 0x3db504f3, v42
.LBB0_306:
	s_or_b64 exec, exec, s[72:73]
	v_or_b32_e32 v42, s1, v99
	s_and_b64 s[14:15], s[16:17], s[8:9]
	v_cmp_gt_i32_e32 vcc, s10, v42
	s_and_b64 s[14:15], s[14:15], vcc
	s_and_saveexec_b64 s[72:73], s[14:15]
	s_cbranch_execz .LBB0_308
	v_mov_b32_e32 v40, v215
	v_fmac_f32_e32 v40, 0x3db504f3, v43
; __device__ __forceinline__ void attnA_item(const Frame& F, const Args& a, int item) {
;     ...
;     for (int ct = 0; ct < 12; ++ct)
; #pragma unroll
;         for (int j = 0; j < 4; ++j) { const int kk = 16 * ct + 4 * fq + j; const int rel = kk - 64 - qq; const int kp = kpw + kk;
;             const bool valid = (rel >= -64) && (rel <= 64) && (kp >= 0) && (kp < L);
;             const float bias = tab[valid ? rel + 64 : 64];
;             const float l = valid ? s[ct][j] * scale + bias : -1e30f; s[ct][j] = l; mx = fmaxf(mx, l); }
.LBB0_308:
	s_or_b64 exec, exec, s[72:73]
	v_or_b32_e32 v42, s1, v101
	s_and_b64 s[14:15], s[18:19], s[8:9]
	v_cmp_gt_i32_e32 vcc, s10, v42
	s_and_b64 s[14:15], s[14:15], vcc
	v_mov_b32_e32 v42, 0xf149f2ca
	v_mov_b32_e32 v43, 0xf149f2ca
	s_and_saveexec_b64 s[72:73], s[14:15]
	s_cbranch_execz .LBB0_310
	v_mov_b32_e32 v43, v216
	v_fmac_f32_e32 v43, 0x3db504f3, v36
.LBB0_310:
	s_or_b64 exec, exec, s[72:73]
	v_or_b32_e32 v36, s1, v103
	s_and_b64 s[14:15], s[74:75], s[8:9]
	v_cmp_gt_i32_e32 vcc, s10, v36
	s_and_b64 s[14:15], s[14:15], vcc
	s_and_saveexec_b64 s[72:73], s[14:15]
	s_cbranch_execz .LBB0_312
	v_mov_b32_e32 v42, v217
	v_fmac_f32_e32 v42, 0x3db504f3, v37
.LBB0_312:
	s_or_b64 exec, exec, s[72:73]
	v_or_b32_e32 v36, s1, v105
	s_and_b64 s[14:15], s[76:77], s[8:9]
	v_cmp_gt_i32_e32 vcc, s10, v36
	s_and_b64 s[14:15], s[14:15], vcc
	v_mov_b32_e32 v36, 0xf149f2ca
	v_mov_b32_e32 v37, 0xf149f2ca
	s_and_saveexec_b64 s[72:73], s[14:15]
	s_cbranch_execz .LBB0_314
	v_mov_b32_e32 v37, v218
	v_fmac_f32_e32 v37, 0x3db504f3, v38
.LBB0_314:
	s_or_b64 exec, exec, s[72:73]
	v_or_b32_e32 v38, s1, v107
	s_and_b64 s[14:15], s[84:85], s[8:9]
	v_cmp_gt_i32_e32 vcc, s10, v38
	s_and_b64 s[14:15], s[14:15], vcc
	s_and_saveexec_b64 s[72:73], s[14:15]
	s_cbranch_execz .LBB0_316
	v_mov_b32_e32 v36, v219
	v_fmac_f32_e32 v36, 0x3db504f3, v39
.LBB0_316:
	s_or_b64 exec, exec, s[72:73]
	v_or_b32_e32 v38, s1, v109
	s_and_b64 s[14:15], s[88:89], s[8:9]
	v_cmp_gt_i32_e32 vcc, s10, v38
	s_and_b64 s[14:15], s[14:15], vcc
	v_mov_b32_e32 v38, 0xf149f2ca
	v_mov_b32_e32 v39, 0xf149f2ca
	s_and_saveexec_b64 s[72:73], s[14:15]
	s_cbranch_execz .LBB0_318
	v_mov_b32_e32 v39, v220
	v_fmac_f32_e32 v39, 0x3db504f3, v32
.LBB0_318:
	s_or_b64 exec, exec, s[72:73]
	v_or_b32_e32 v32, s1, v111
	s_and_b64 s[14:15], s[28:29], s[8:9]
	v_cmp_gt_i32_e32 vcc, s10, v32
	s_and_b64 s[14:15], s[14:15], vcc
	s_and_saveexec_b64 s[72:73], s[14:15]
	s_cbranch_execz .LBB0_320
	v_mov_b32_e32 v38, v221
	v_fmac_f32_e32 v38, 0x3db504f3, v33
.LBB0_320:
	s_or_b64 exec, exec, s[72:73]
	v_or_b32_e32 v32, s1, v113
	s_and_b64 s[14:15], s[30:31], s[8:9]
	v_cmp_gt_i32_e32 vcc, s10, v32
	s_and_b64 s[14:15], s[14:15], vcc
	v_mov_b32_e32 v32, 0xf149f2ca
	v_mov_b32_e32 v33, 0xf149f2ca
	s_and_saveexec_b64 s[72:73], s[14:15]
	s_cbranch_execz .LBB0_322
	v_mov_b32_e32 v33, v222
	v_fmac_f32_e32 v33, 0x3db504f3, v34
.LBB0_322:
	s_or_b64 exec, exec, s[72:73]
	v_or_b32_e32 v34, s1, v115
	s_and_b64 s[8:9], s[34:35], s[8:9]
	v_cmp_gt_i32_e32 vcc, s10, v34
	s_and_b64 s[14:15], s[8:9], vcc
	s_and_saveexec_b64 s[8:9], s[14:15]
	s_cbranch_execz .LBB0_324
	v_mov_b32_e32 v32, v223
	v_fmac_f32_e32 v32, 0x3db504f3, v35
.LBB0_324:
	s_or_b64 exec, exec, s[8:9]
	v_or_b32_e32 v34, s12, v68
	v_cmp_gt_u32_e32 vcc, s10, v34
	v_mov_b32_e32 v35, 0xf149f2ca
	v_mov_b32_e32 v50, 0xf149f2ca
	s_and_saveexec_b64 s[8:9], vcc
	s_cbranch_execz .LBB0_326
	v_mov_b32_e32 v50, v224
	v_fmac_f32_e32 v50, 0x3db504f3, v20
.LBB0_326:
	s_or_b64 exec, exec, s[8:9]
	v_add_u32_e32 v20, s1, v118
	v_cmp_gt_i32_e32 vcc, s10, v20
	s_and_saveexec_b64 s[8:9], vcc
	s_cbranch_execz .LBB0_328
	v_mov_b32_e32 v35, v225
	v_fmac_f32_e32 v35, 0x3db504f3, v21
.LBB0_328:
	s_or_b64 exec, exec, s[8:9]
	v_add_u32_e32 v20, s1, v120
	v_cmp_gt_i32_e32 vcc, s10, v20
	v_mov_b32_e32 v20, 0xf149f2ca
	v_mov_b32_e32 v21, 0xf149f2ca
	s_and_saveexec_b64 s[8:9], vcc
	s_cbranch_execz .LBB0_330
	v_mov_b32_e32 v21, v226
	v_fmac_f32_e32 v21, 0x3db504f3, v22
.LBB0_330:
	s_or_b64 exec, exec, s[8:9]
	v_add_u32_e32 v22, s1, v122
	v_cmp_gt_i32_e32 vcc, s10, v22
	s_and_saveexec_b64 s[8:9], vcc
	s_cbranch_execz .LBB0_332
	v_mov_b32_e32 v20, v227
	v_fmac_f32_e32 v20, 0x3db504f3, v23
.LBB0_332:
	s_or_b64 exec, exec, s[8:9]
	v_add_u32_e32 v22, s1, v124
	v_cmp_gt_i32_e32 vcc, s10, v22
	v_mov_b32_e32 v22, 0xf149f2ca
	v_mov_b32_e32 v23, 0xf149f2ca
	s_and_saveexec_b64 s[8:9], vcc
	s_cbranch_execz .LBB0_334
	v_mov_b32_e32 v23, v228
	v_fmac_f32_e32 v23, 0x3db504f3, v16
.LBB0_334:
	s_or_b64 exec, exec, s[8:9]
	v_add_u32_e32 v16, s1, v126
	v_cmp_gt_i32_e32 vcc, s10, v16
	s_and_saveexec_b64 s[8:9], vcc
	s_cbranch_execz .LBB0_336
	v_mov_b32_e32 v22, v229
	v_fmac_f32_e32 v22, 0x3db504f3, v17
.LBB0_336:
	s_or_b64 exec, exec, s[8:9]
	v_add_u32_e32 v16, s1, v128
	v_cmp_gt_i32_e32 vcc, s10, v16
	v_mov_b32_e32 v16, 0xf149f2ca
	v_mov_b32_e32 v17, 0xf149f2ca
	s_and_saveexec_b64 s[8:9], vcc
	s_cbranch_execz .LBB0_338
	v_mov_b32_e32 v17, v230
	v_fmac_f32_e32 v17, 0x3db504f3, v18
.LBB0_338:
	s_or_b64 exec, exec, s[8:9]
	v_add_u32_e32 v18, s1, v130
	v_cmp_gt_i32_e32 vcc, s10, v18
	s_and_saveexec_b64 s[8:9], vcc
	s_cbranch_execz .LBB0_340
	v_mov_b32_e32 v16, v231
	v_fmac_f32_e32 v16, 0x3db504f3, v19
.LBB0_340:
	s_or_b64 exec, exec, s[8:9]
	v_add_u32_e32 v18, s1, v132
	v_cmp_gt_i32_e32 vcc, s10, v18
	v_mov_b32_e32 v18, 0xf149f2ca
	v_mov_b32_e32 v19, 0xf149f2ca
	s_and_saveexec_b64 s[8:9], vcc
	s_cbranch_execz .LBB0_342
	v_mov_b32_e32 v19, v232
	v_fmac_f32_e32 v19, 0x3db504f3, v28
.LBB0_342:
	s_or_b64 exec, exec, s[8:9]
	v_add_u32_e32 v28, s1, v134
	v_cmp_gt_i32_e32 vcc, s10, v28
	s_and_saveexec_b64 s[8:9], vcc
	s_cbranch_execz .LBB0_344
	v_mov_b32_e32 v18, v233
	v_fmac_f32_e32 v18, 0x3db504f3, v29
.LBB0_344:
	s_or_b64 exec, exec, s[8:9]
	v_add_u32_e32 v28, s1, v136
	v_cmp_gt_i32_e32 vcc, s10, v28
	v_mov_b32_e32 v28, 0xf149f2ca
	v_mov_b32_e32 v29, 0xf149f2ca
	s_and_saveexec_b64 s[8:9], vcc
	s_cbranch_execz .LBB0_346
	v_mov_b32_e32 v29, v234
	v_fmac_f32_e32 v29, 0x3db504f3, v30
; __device__ __forceinline__ void attnA_item(const Frame& F, const Args& a, int item) {
;     ...
;     for (int ct = 0; ct < 12; ++ct)
; #pragma unroll
;         for (int j = 0; j < 4; ++j) { const int kk = 16 * ct + 4 * fq + j; const int rel = kk - 64 - qq; const int kp = kpw + kk;
;             const bool valid = (rel >= -64) && (rel <= 64) && (kp >= 0) && (kp < L);
;             const float bias = tab[valid ? rel + 64 : 64];
;             const float l = valid ? s[ct][j] * scale + bias : -1e30f; s[ct][j] = l; mx = fmaxf(mx, l); }
.LBB0_346:
	s_or_b64 exec, exec, s[8:9]
	v_add_u32_e32 v30, s1, v138
	v_cmp_gt_i32_e32 vcc, s10, v30
	s_and_saveexec_b64 s[8:9], vcc
	s_cbranch_execz .LBB0_348
	v_mov_b32_e32 v28, v235
	v_fmac_f32_e32 v28, 0x3db504f3, v31
.LBB0_348:
	s_or_b64 exec, exec, s[8:9]
	v_add_u32_e32 v30, s1, v140
	v_cmp_gt_i32_e32 vcc, s10, v30
	v_mov_b32_e32 v30, 0xf149f2ca
	v_mov_b32_e32 v31, 0xf149f2ca
	s_and_saveexec_b64 s[8:9], vcc
	s_cbranch_execz .LBB0_350
	v_mov_b32_e32 v31, v236
	v_fmac_f32_e32 v31, 0x3db504f3, v24
.LBB0_350:
	s_or_b64 exec, exec, s[8:9]
	v_add_u32_e32 v24, s1, v142
	v_cmp_gt_i32_e32 vcc, s10, v24
	s_and_saveexec_b64 s[8:9], vcc
	s_cbranch_execz .LBB0_352
	v_mov_b32_e32 v30, v237
	v_fmac_f32_e32 v30, 0x3db504f3, v25
.LBB0_352:
	s_or_b64 exec, exec, s[8:9]
	v_add_u32_e32 v24, s1, v145
	v_cmp_gt_i32_e32 vcc, s10, v24
	v_mov_b32_e32 v24, 0xf149f2ca
	v_mov_b32_e32 v25, 0xf149f2ca
	s_and_saveexec_b64 s[8:9], vcc
	s_cbranch_execz .LBB0_354
	v_mov_b32_e32 v25, v238
	v_fmac_f32_e32 v25, 0x3db504f3, v26
.LBB0_354:
	s_or_b64 exec, exec, s[8:9]
	v_add_u32_e32 v26, s1, v147
	v_cmp_gt_i32_e32 vcc, s10, v26
	s_and_saveexec_b64 s[8:9], vcc
	s_cbranch_execz .LBB0_356
	v_mov_b32_e32 v24, v239
	v_fmac_f32_e32 v24, 0x3db504f3, v27
.LBB0_356:
	s_or_b64 exec, exec, s[8:9]
	v_add_u32_e32 v26, s1, v149
	v_cmp_gt_i32_e32 vcc, s10, v26
	s_and_b64 s[12:13], s[36:37], vcc
	v_mov_b32_e32 v26, 0xf149f2ca
	v_mov_b32_e32 v27, 0xf149f2ca
	s_and_saveexec_b64 s[8:9], s[12:13]
	s_cbranch_execz .LBB0_358
	v_mov_b32_e32 v27, v240
	v_fmac_f32_e32 v27, 0x3db504f3, v12
.LBB0_358:
	s_or_b64 exec, exec, s[8:9]
	v_add_u32_e32 v12, s1, v151
	v_cmp_gt_i32_e32 vcc, s10, v12
	s_and_b64 s[12:13], s[38:39], vcc
	s_and_saveexec_b64 s[8:9], s[12:13]
	s_cbranch_execz .LBB0_360
	v_mov_b32_e32 v26, v241
	v_fmac_f32_e32 v26, 0x3db504f3, v13
.LBB0_360:
	s_or_b64 exec, exec, s[8:9]
	v_add_u32_e32 v12, s1, v153
	v_cmp_gt_i32_e32 vcc, s10, v12
	s_and_b64 s[12:13], s[40:41], vcc
	v_mov_b32_e32 v12, 0xf149f2ca
	v_mov_b32_e32 v13, 0xf149f2ca
	s_and_saveexec_b64 s[8:9], s[12:13]
	s_cbranch_execz .LBB0_362
	v_mov_b32_e32 v13, v244
	v_fmac_f32_e32 v13, 0x3db504f3, v14
.LBB0_362:
	s_or_b64 exec, exec, s[8:9]
	v_add_u32_e32 v14, s1, v155
	v_cmp_gt_i32_e32 vcc, s10, v14
	s_and_b64 s[12:13], s[42:43], vcc
	s_and_saveexec_b64 s[8:9], s[12:13]
	s_cbranch_execz .LBB0_364
	v_mov_b32_e32 v12, v245
	v_fmac_f32_e32 v12, 0x3db504f3, v15
.LBB0_364:
	s_or_b64 exec, exec, s[8:9]
	v_add_u32_e32 v14, s1, v157
	v_cmp_gt_i32_e32 vcc, s10, v14
	s_and_b64 s[12:13], s[44:45], vcc
	v_mov_b32_e32 v14, 0xf149f2ca
	v_mov_b32_e32 v15, 0xf149f2ca
	s_and_saveexec_b64 s[8:9], s[12:13]
	s_cbranch_execz .LBB0_366
	v_mov_b32_e32 v15, v246
	v_fmac_f32_e32 v15, 0x3db504f3, v8
.LBB0_366:
	s_or_b64 exec, exec, s[8:9]
	v_add_u32_e32 v8, s1, v159
	v_cmp_gt_i32_e32 vcc, s10, v8
	s_and_b64 s[12:13], s[46:47], vcc
	s_and_saveexec_b64 s[8:9], s[12:13]
	s_cbranch_execz .LBB0_368
	v_mov_b32_e32 v14, v247
	v_fmac_f32_e32 v14, 0x3db504f3, v9
.LBB0_368:
	s_or_b64 exec, exec, s[8:9]
	v_add_u32_e32 v8, s1, v161
	v_cmp_gt_i32_e32 vcc, s10, v8
	s_and_b64 s[12:13], s[48:49], vcc
	v_mov_b32_e32 v8, 0xf149f2ca
	v_mov_b32_e32 v9, 0xf149f2ca
	s_and_saveexec_b64 s[8:9], s[12:13]
	s_cbranch_execz .LBB0_370
	v_mov_b32_e32 v9, v248
	v_fmac_f32_e32 v9, 0x3db504f3, v10
.LBB0_370:
	s_or_b64 exec, exec, s[8:9]
	v_add_u32_e32 v10, s1, v163
	v_cmp_gt_i32_e32 vcc, s10, v10
	s_and_b64 s[12:13], s[50:51], vcc
	s_and_saveexec_b64 s[8:9], s[12:13]
	s_cbranch_execz .LBB0_372
	v_mov_b32_e32 v8, v249
	v_fmac_f32_e32 v8, 0x3db504f3, v11
.LBB0_372:
	s_or_b64 exec, exec, s[8:9]
	v_add_u32_e32 v10, s1, v165
	v_cmp_gt_i32_e32 vcc, s10, v10
	s_and_b64 s[12:13], s[52:53], vcc
	v_mov_b32_e32 v10, 0xf149f2ca
	v_mov_b32_e32 v11, 0xf149f2ca
	s_and_saveexec_b64 s[8:9], s[12:13]
	s_cbranch_execz .LBB0_374
	v_mov_b32_e32 v11, v250
	v_fmac_f32_e32 v11, 0x3db504f3, v4
.LBB0_374:
	s_or_b64 exec, exec, s[8:9]
	v_add_u32_e32 v4, s1, v167
	v_cmp_gt_i32_e32 vcc, s10, v4
	s_and_b64 s[12:13], s[54:55], vcc
	s_and_saveexec_b64 s[8:9], s[12:13]
	s_cbranch_execz .LBB0_376
	v_mov_b32_e32 v10, v251
	v_fmac_f32_e32 v10, 0x3db504f3, v5
.LBB0_376:
	s_or_b64 exec, exec, s[8:9]
	v_add_u32_e32 v4, s1, v169
	v_cmp_gt_i32_e32 vcc, s10, v4
	s_and_b64 s[12:13], s[56:57], vcc
	v_mov_b32_e32 v4, 0xf149f2ca
	v_mov_b32_e32 v5, 0xf149f2ca
	s_and_saveexec_b64 s[8:9], s[12:13]
	s_cbranch_execz .LBB0_378
	v_mov_b32_e32 v5, v252
	v_fmac_f32_e32 v5, 0x3db504f3, v6
.LBB0_378:
	s_or_b64 exec, exec, s[8:9]
	v_add_u32_e32 v6, s1, v171
	v_cmp_gt_i32_e32 vcc, s10, v6
	s_and_b64 s[12:13], s[58:59], vcc
	s_and_saveexec_b64 s[8:9], s[12:13]
	s_cbranch_execz .LBB0_380
	v_mov_b32_e32 v4, v253
	v_fmac_f32_e32 v4, 0x3db504f3, v7
.LBB0_380:
	s_or_b64 exec, exec, s[8:9]
	v_add_u32_e32 v6, s1, v173
	v_cmp_gt_i32_e32 vcc, s10, v6
	s_and_b64 s[12:13], s[60:61], vcc
	v_mov_b32_e32 v6, 0xf149f2ca
	v_mov_b32_e32 v7, 0xf149f2ca
	s_and_saveexec_b64 s[8:9], s[12:13]
	s_cbranch_execz .LBB0_382
	v_mov_b32_e32 v7, v254
	v_fmac_f32_e32 v7, 0x3db504f3, v0
.LBB0_382:
	s_or_b64 exec, exec, s[8:9]
	v_add_u32_e32 v0, s1, v175
	v_cmp_gt_i32_e32 vcc, s10, v0
	s_and_b64 s[12:13], s[62:63], vcc
	s_and_saveexec_b64 s[8:9], s[12:13]
	s_cbranch_execz .LBB0_384
	v_mov_b32_e32 v6, v255
	v_fmac_f32_e32 v6, 0x3db504f3, v1

; #define LAS __attribute__((address_space(3)))
; template <int NCT>
; __device__ __forceinline__ void qk_accum(f32x4 (&s)[NCT], const LAS unsigned char* Kt, int key_row0, const bf16x8 (&qf)[4], int fr, int fq) {
; #pragma unroll
;     for (int ct = 0; ct < NCT; ++ct)
; #pragma unroll
;         for (int ks = 0; ks < 4; ++ks) { const bf16x8 kf = *(const LAS bf16x8*)(Kt + (key_row0 + 16 * ct + fr) * AT_PITCH + 64 * ks + 16 * fq);
;             s[ct] = __builtin_amdgcn_mfma_f32_16x16x32_bf16(kf, qf[ks], s[ct], 0, 0, 0); if (ks == 3 && (ct & 1)) asm volatile("" ::: "memory"); }
; }
; __device__ __forceinline__ void attnA_item(const Frame& F, const Args& a, int item) {
;     ...
;     const int qq = 16 * (F.wave & 3) + fr;
;     const int qpos = (n0 + hb) * 64 + qq;
;     const size_t qrow = rowbase + (size_t)qpos * d + r;
;     bf16x8 qf[4];
; #pragma unroll
;     for (int ks = 0; ks < 4; ++ks) qf[ks] = *(const bf16x8*)(proj + qrow * NIN + C_Q + h * 128 + 32 * ks + 8 * fq);
;     __syncthreads();
;     f32x4 s[12];
; #pragma unroll
;     for (int ct = 0; ct < 12; ++ct) s[ct] = (f32x4){0.f, 0.f, 0.f, 0.f};
;     qk_accum<12>(s, R0, 64 * hb, qf, fr, fq);
.LBB0_468:
	s_or_b64 exec, exec, s[72:73]
	s_add_i32 s12, s12, s95
	v_or_b32_e32 v66, s12, v86
	v_lshlrev_b64 v[0:1], s11, v[66:67]
	v_lshl_add_u64 v[60:61], v[0:1], 0, s[8:9]
	v_mov_b64_e32 v[0:1], s[96:97]
	v_mad_u64_u32 v[0:1], s[8:9], v60, s93, v[0:1]
	v_mov_b32_e32 v2, v1
	v_mad_u64_u32 v[2:3], s[8:9], v61, s93, v[2:3]
	v_mov_b32_e32 v1, v2
	v_lshl_add_u64 v[0:1], s[2:3], 1, v[0:1]
	v_mov_b32_e32 v71, v67
	v_lshl_add_u64 v[0:1], v[0:1], 0, v[70:71]
	global_load_dwordx4 v[56:59], v[0:1], off
	global_load_dwordx4 v[52:55], v[0:1], off offset:64
	global_load_dwordx4 v[48:51], v[0:1], off offset:128
	s_nop 0
	global_load_dwordx4 v[0:3], v[0:1], off offset:192
	s_waitcnt lgkmcnt(0)
	s_barrier
	s_sub_i32 s3, s12, 64
	s_cmp_lg_u32 s12, 0
	v_readlane_b32 s14, v242, 44
	s_cselect_b64 s[8:9], -1, 0
	v_readlane_b32 s15, v242, 45
	s_and_b64 s[14:15], s[14:15], s[8:9]
	ds_read_b128 v[208:211], v196
	ds_read_b128 v[212:215], v196 offset:64
	ds_read_b128 v[216:219], v196 offset:128
	ds_read_b128 v[220:223], v196 offset:192
	ds_read_b128 v[224:227], v196 offset:4352
	ds_read_b128 v[228:231], v196 offset:4416
	ds_read_b128 v[232:235], v196 offset:4480
	ds_read_b128 v[236:239], v196 offset:4544
	ds_read_b128 v[244:247], v196 offset:8704
	ds_read_b128 v[248:251], v196 offset:8768
	ds_read_b128 v[252:255], v196 offset:8832
	s_waitcnt vmcnt(0)
	s_waitcnt lgkmcnt(10)
	v_mfma_f32_16x16x32_bf16 v[4:7], v[208:211], v[56:59], 0
	ds_read_b128 v[208:211], v196 offset:8896
	s_waitcnt lgkmcnt(10)
	v_mfma_f32_16x16x32_bf16 v[4:7], v[212:215], v[52:55], v[4:7]
	ds_read_b128 v[212:215], v196 offset:13056
	s_waitcnt lgkmcnt(10)
	v_mfma_f32_16x16x32_bf16 v[4:7], v[216:219], v[48:51], v[4:7]
	ds_read_b128 v[216:219], v196 offset:13120
	s_waitcnt lgkmcnt(10)
	v_mfma_f32_16x16x32_bf16 v[44:47], v[220:223], v[0:3], v[4:7]
	ds_read_b128 v[220:223], v196 offset:13184
	s_waitcnt lgkmcnt(10)
	v_mfma_f32_16x16x32_bf16 v[4:7], v[224:227], v[56:59], 0
	ds_read_b128 v[224:227], v196 offset:13248
	s_waitcnt lgkmcnt(10)
	v_mfma_f32_16x16x32_bf16 v[4:7], v[228:231], v[52:55], v[4:7]
	ds_read_b128 v[228:231], v196 offset:17408
	s_waitcnt lgkmcnt(10)
	v_mfma_f32_16x16x32_bf16 v[4:7], v[232:235], v[48:51], v[4:7]
	ds_read_b128 v[232:235], v196 offset:17472
	s_waitcnt lgkmcnt(10)
	v_mfma_f32_16x16x32_bf16 v[40:43], v[236:239], v[0:3], v[4:7]
	ds_read_b128 v[236:239], v196 offset:17536
	s_waitcnt lgkmcnt(10)
	v_mfma_f32_16x16x32_bf16 v[4:7], v[244:247], v[56:59], 0
	ds_read_b128 v[244:247], v196 offset:17600
	s_waitcnt lgkmcnt(10)
	v_mfma_f32_16x16x32_bf16 v[4:7], v[248:251], v[52:55], v[4:7]
	ds_read_b128 v[248:251], v196 offset:21760
	s_waitcnt lgkmcnt(10)
	v_mfma_f32_16x16x32_bf16 v[4:7], v[252:255], v[48:51], v[4:7]
	ds_read_b128 v[252:255], v196 offset:21824
	s_waitcnt lgkmcnt(10)
	v_mfma_f32_16x16x32_bf16 v[36:39], v[208:211], v[0:3], v[4:7]
	ds_read_b128 v[208:211], v196 offset:21888
	s_waitcnt lgkmcnt(10)
	v_mfma_f32_16x16x32_bf16 v[4:7], v[212:215], v[56:59], 0
	ds_read_b128 v[212:215], v196 offset:21952
	s_waitcnt lgkmcnt(10)
	v_mfma_f32_16x16x32_bf16 v[4:7], v[216:219], v[52:55], v[4:7]
	ds_read_b128 v[216:219], v196 offset:26112
	s_waitcnt lgkmcnt(10)
	v_mfma_f32_16x16x32_bf16 v[4:7], v[220:223], v[48:51], v[4:7]
	ds_read_b128 v[220:223], v196 offset:26176
	s_waitcnt lgkmcnt(10)
	v_mfma_f32_16x16x32_bf16 v[32:35], v[224:227], v[0:3], v[4:7]
	ds_read_b128 v[224:227], v196 offset:26240
	s_waitcnt lgkmcnt(10)
	v_mfma_f32_16x16x32_bf16 v[4:7], v[228:231], v[56:59], 0
	ds_read_b128 v[228:231], v196 offset:26304
	s_waitcnt lgkmcnt(10)
	v_mfma_f32_16x16x32_bf16 v[4:7], v[232:235], v[52:55], v[4:7]
	ds_read_b128 v[232:235], v196 offset:30464
	s_waitcnt lgkmcnt(10)
	v_mfma_f32_16x16x32_bf16 v[4:7], v[236:239], v[48:51], v[4:7]
	ds_read_b128 v[236:239], v196 offset:30528
	s_waitcnt lgkmcnt(10)
	v_mfma_f32_16x16x32_bf16 v[20:23], v[244:247], v[0:3], v[4:7]
	ds_read_b128 v[244:247], v196 offset:30592
	s_waitcnt lgkmcnt(10)
	v_mfma_f32_16x16x32_bf16 v[4:7], v[248:251], v[56:59], 0
	ds_read_b128 v[248:251], v196 offset:30656
	s_waitcnt lgkmcnt(10)
	v_mfma_f32_16x16x32_bf16 v[4:7], v[252:255], v[52:55], v[4:7]
	ds_read_b128 v[252:255], v196 offset:34816
	s_waitcnt lgkmcnt(10)
	v_mfma_f32_16x16x32_bf16 v[4:7], v[208:211], v[48:51], v[4:7]
	ds_read_b128 v[208:211], v196 offset:34880
	s_waitcnt lgkmcnt(10)
	v_mfma_f32_16x16x32_bf16 v[16:19], v[212:215], v[0:3], v[4:7]
	ds_read_b128 v[212:215], v196 offset:34944
	s_waitcnt lgkmcnt(10)
	v_mfma_f32_16x16x32_bf16 v[4:7], v[216:219], v[56:59], 0
	ds_read_b128 v[216:219], v196 offset:35008
	s_waitcnt lgkmcnt(10)
	v_mfma_f32_16x16x32_bf16 v[4:7], v[220:223], v[52:55], v[4:7]
	ds_read_b128 v[220:223], v196 offset:39168
	s_waitcnt lgkmcnt(10)
	v_mfma_f32_16x16x32_bf16 v[4:7], v[224:227], v[48:51], v[4:7]
	ds_read_b128 v[224:227], v196 offset:39232
	s_waitcnt lgkmcnt(10)
	v_mfma_f32_16x16x32_bf16 v[28:31], v[228:231], v[0:3], v[4:7]
	ds_read_b128 v[228:231], v196 offset:39296
	s_waitcnt lgkmcnt(10)
	v_mfma_f32_16x16x32_bf16 v[4:7], v[232:235], v[56:59], 0
	ds_read_b128 v[232:235], v196 offset:39360
	s_waitcnt lgkmcnt(10)
	v_mfma_f32_16x16x32_bf16 v[4:7], v[236:239], v[52:55], v[4:7]
	ds_read_b128 v[236:239], v196 offset:43584
	s_waitcnt lgkmcnt(10)
	v_mfma_f32_16x16x32_bf16 v[4:7], v[244:247], v[48:51], v[4:7]
	ds_read_b128 v[244:247], v196 offset:43520
	s_waitcnt lgkmcnt(10)
	v_mfma_f32_16x16x32_bf16 v[24:27], v[248:251], v[0:3], v[4:7]
	ds_read_b128 v[248:251], v196 offset:43648
	s_waitcnt lgkmcnt(10)
	v_mfma_f32_16x16x32_bf16 v[4:7], v[252:255], v[56:59], 0
	ds_read_b128 v[252:255], v196 offset:43712
	s_waitcnt lgkmcnt(10)
; __device__ __forceinline__ void attnA_item(const Frame& F, const Args& a, int item) {
;     ...
;     for (int ct = 0; ct < 12; ++ct)
; #pragma unroll
;         for (int j = 0; j < 4; ++j) { const int kk = 16 * ct + 4 * fq + j; const int rel = kk - 64 - qq; const int kp = kpw + kk;
;             const bool valid = (rel >= -64) && (rel <= 64) && (kp >= 0) && (kp < L);
;             const float bias = tab[valid ? rel + 64 : 64];
;             const float l = valid ? s[ct][j] * scale + bias : -1e30f; s[ct][j] = l; mx = fmaxf(mx, l); }
	v_mfma_f32_16x16x32_bf16 v[4:7], v[208:211], v[52:55], v[4:7]
	ds_read_b128 v[208:211], v196 offset:47872
	s_waitcnt lgkmcnt(10)
	v_mfma_f32_16x16x32_bf16 v[4:7], v[212:215], v[48:51], v[4:7]
	ds_read_b128 v[212:215], v196 offset:47936
	s_waitcnt lgkmcnt(10)
	v_mfma_f32_16x16x32_bf16 v[12:15], v[216:219], v[0:3], v[4:7]
	ds_read_b128 v[216:219], v196 offset:48000
	s_waitcnt lgkmcnt(10)
	v_mfma_f32_16x16x32_bf16 v[4:7], v[220:223], v[56:59], 0
	ds_read_b128 v[220:223], v196 offset:48064
	s_waitcnt lgkmcnt(10)
	v_mfma_f32_16x16x32_bf16 v[4:7], v[224:227], v[52:55], v[4:7]
	s_waitcnt lgkmcnt(9)
	v_mfma_f32_16x16x32_bf16 v[4:7], v[228:231], v[48:51], v[4:7]
	s_waitcnt lgkmcnt(8)
	v_mfma_f32_16x16x32_bf16 v[8:11], v[232:235], v[0:3], v[4:7]
	s_waitcnt lgkmcnt(6)
	v_mfma_f32_16x16x32_bf16 v[4:7], v[244:247], v[56:59], 0
	s_waitcnt lgkmcnt(7)
	v_mfma_f32_16x16x32_bf16 v[4:7], v[236:239], v[52:55], v[4:7]
	s_waitcnt lgkmcnt(5)
	v_mfma_f32_16x16x32_bf16 v[4:7], v[248:251], v[48:51], v[4:7]
	s_waitcnt lgkmcnt(4)
	v_mfma_f32_16x16x32_bf16 v[4:7], v[252:255], v[0:3], v[4:7]
	s_waitcnt lgkmcnt(3)
	v_mfma_f32_16x16x32_bf16 v[56:59], v[208:211], v[56:59], 0
	s_waitcnt lgkmcnt(2)
	v_mfma_f32_16x16x32_bf16 v[52:55], v[212:215], v[52:55], v[56:59]
	s_waitcnt lgkmcnt(1)
	v_mfma_f32_16x16x32_bf16 v[48:51], v[216:219], v[48:51], v[52:55]
	s_waitcnt lgkmcnt(0)
	v_mfma_f32_16x16x32_bf16 v[0:3], v[220:223], v[0:3], v[48:51]
	s_nop 2
	ds_read_b32 v208, v87
	ds_read_b32 v209, v89
	ds_read_b32 v210, v91
	ds_read_b32 v211, v93
	ds_read_b32 v212, v95
	ds_read_b32 v213, v97
	ds_read_b32 v214, v99
	ds_read_b32 v215, v101
	ds_read_b32 v216, v103
	ds_read_b32 v217, v105
	ds_read_b32 v218, v107
	ds_read_b32 v219, v109
	ds_read_b32 v220, v111
	ds_read_b32 v221, v113
	ds_read_b32 v222, v115
	ds_read_b32 v223, v117
	ds_read_b32 v224, v118
	ds_read_b32 v225, v120
	ds_read_b32 v226, v122
	ds_read_b32 v227, v124
	ds_read_b32 v228, v126
	ds_read_b32 v229, v128
	ds_read_b32 v230, v130
	ds_read_b32 v231, v132
	ds_read_b32 v232, v134
	ds_read_b32 v233, v136
	ds_read_b32 v234, v138
	ds_read_b32 v235, v140
	ds_read_b32 v236, v142
	ds_read_b32 v237, v145
	ds_read_b32 v238, v147
	ds_read_b32 v239, v149
	ds_read_b32 v240, v151
	ds_read_b32 v241, v153
	ds_read_b32 v244, v155
	ds_read_b32 v245, v157
	ds_read_b32 v246, v159
	ds_read_b32 v247, v161
	ds_read_b32 v248, v163
	ds_read_b32 v249, v165
	ds_read_b32 v250, v167
	ds_read_b32 v251, v169
	ds_read_b32 v252, v171
	ds_read_b32 v253, v173
	ds_read_b32 v254, v175
	ds_read_b32 v255, v177
	s_waitcnt lgkmcnt(0)
	v_or_b32_e32 v48, s3, v68
	v_cmp_gt_i32_e32 vcc, s10, v48
	s_and_b64 s[14:15], s[14:15], vcc
	v_mov_b32_e32 v48, 0xf149f2ca
	v_mov_b32_e32 v49, 0xf149f2ca
	s_and_saveexec_b64 s[72:73], s[14:15]
	s_cbranch_execz .LBB0_470
	v_mov_b32_e32 v49, v208
	v_fmac_f32_e32 v49, 0x3db504f3, v44
.LBB0_470:
	s_or_b64 exec, exec, s[72:73]
	v_readlane_b32 s14, v242, 46
	v_or_b32_e32 v44, s3, v88
	v_readlane_b32 s15, v242, 47
	s_and_b64 s[14:15], s[14:15], s[8:9]
	v_cmp_gt_i32_e32 vcc, s10, v44
	s_and_b64 s[14:15], s[14:15], vcc
	s_and_saveexec_b64 s[72:73], s[14:15]
	s_cbranch_execz .LBB0_472
	v_mov_b32_e32 v48, v209
	v_fmac_f32_e32 v48, 0x3db504f3, v45
.LBB0_472:
	s_or_b64 exec, exec, s[72:73]
	v_readlane_b32 s14, v242, 48
	v_or_b32_e32 v44, s3, v90
	v_readlane_b32 s15, v242, 49
	s_and_b64 s[14:15], s[14:15], s[8:9]
	v_cmp_gt_i32_e32 vcc, s10, v44
	s_and_b64 s[14:15], s[14:15], vcc
	v_mov_b32_e32 v44, 0xf149f2ca
	v_mov_b32_e32 v45, 0xf149f2ca
	s_and_saveexec_b64 s[72:73], s[14:15]
	s_cbranch_execz .LBB0_474
	v_mov_b32_e32 v45, v210
	v_fmac_f32_e32 v45, 0x3db504f3, v46
.LBB0_474:
	s_or_b64 exec, exec, s[72:73]
	v_readlane_b32 s14, v242, 50
	v_or_b32_e32 v46, s3, v92
	v_readlane_b32 s15, v242, 51
	s_and_b64 s[14:15], s[14:15], s[8:9]
	v_cmp_gt_i32_e32 vcc, s10, v46
	s_and_b64 s[14:15], s[14:15], vcc
	s_and_saveexec_b64 s[72:73], s[14:15]
	s_cbranch_execz .LBB0_476
	v_mov_b32_e32 v44, v211
	v_fmac_f32_e32 v44, 0x3db504f3, v47
; __device__ __forceinline__ void attnA_item(const Frame& F, const Args& a, int item) {
;     ...
;     for (int ct = 0; ct < 12; ++ct)
; #pragma unroll
;         for (int j = 0; j < 4; ++j) { const int kk = 16 * ct + 4 * fq + j; const int rel = kk - 64 - qq; const int kp = kpw + kk;
;             const bool valid = (rel >= -64) && (rel <= 64) && (kp >= 0) && (kp < L);
;             const float bias = tab[valid ? rel + 64 : 64];
;             const float l = valid ? s[ct][j] * scale + bias : -1e30f; s[ct][j] = l; mx = fmaxf(mx, l); }
.LBB0_476:
	s_or_b64 exec, exec, s[72:73]
	v_readlane_b32 s14, v242, 52
	v_or_b32_e32 v46, s3, v94
	v_readlane_b32 s15, v242, 53
	s_and_b64 s[14:15], s[14:15], s[8:9]
	v_cmp_gt_i32_e32 vcc, s10, v46
	s_and_b64 s[14:15], s[14:15], vcc
	v_mov_b32_e32 v46, 0xf149f2ca
	v_mov_b32_e32 v47, 0xf149f2ca
	s_and_saveexec_b64 s[72:73], s[14:15]
	s_cbranch_execz .LBB0_478
	v_mov_b32_e32 v47, v212
	v_fmac_f32_e32 v47, 0x3db504f3, v40
.LBB0_478:
	s_or_b64 exec, exec, s[72:73]
	v_readlane_b32 s14, v242, 54
	v_or_b32_e32 v40, s3, v96
	v_readlane_b32 s15, v242, 55
	s_and_b64 s[14:15], s[14:15], s[8:9]
	v_cmp_gt_i32_e32 vcc, s10, v40
	s_and_b64 s[14:15], s[14:15], vcc
	s_and_saveexec_b64 s[72:73], s[14:15]
	s_cbranch_execz .LBB0_480
	v_mov_b32_e32 v46, v213
	v_fmac_f32_e32 v46, 0x3db504f3, v41
.LBB0_480:
	s_or_b64 exec, exec, s[72:73]
	v_readlane_b32 s14, v242, 56
	v_or_b32_e32 v40, s3, v98
	v_readlane_b32 s15, v242, 57
	s_and_b64 s[14:15], s[14:15], s[8:9]
	v_cmp_gt_i32_e32 vcc, s10, v40
	s_and_b64 s[14:15], s[14:15], vcc
	v_mov_b32_e32 v40, 0xf149f2ca
	v_mov_b32_e32 v41, 0xf149f2ca
	s_and_saveexec_b64 s[72:73], s[14:15]
	s_cbranch_execz .LBB0_482
	v_mov_b32_e32 v41, v214
	v_fmac_f32_e32 v41, 0x3db504f3, v42
.LBB0_482:
	s_or_b64 exec, exec, s[72:73]
	v_or_b32_e32 v42, s3, v100
	s_and_b64 s[14:15], s[16:17], s[8:9]
	v_cmp_gt_i32_e32 vcc, s10, v42
	s_and_b64 s[14:15], s[14:15], vcc
	s_and_saveexec_b64 s[72:73], s[14:15]
	s_cbranch_execz .LBB0_484
	v_mov_b32_e32 v40, v215
	v_fmac_f32_e32 v40, 0x3db504f3, v43
.LBB0_484:
	s_or_b64 exec, exec, s[72:73]
	v_or_b32_e32 v42, s3, v102
	s_and_b64 s[14:15], s[18:19], s[8:9]
	v_cmp_gt_i32_e32 vcc, s10, v42
	s_and_b64 s[14:15], s[14:15], vcc
	v_mov_b32_e32 v42, 0xf149f2ca
	v_mov_b32_e32 v43, 0xf149f2ca
	s_and_saveexec_b64 s[72:73], s[14:15]
	s_cbranch_execz .LBB0_486
	v_mov_b32_e32 v43, v216
	v_fmac_f32_e32 v43, 0x3db504f3, v36
.LBB0_486:
	s_or_b64 exec, exec, s[72:73]
	v_or_b32_e32 v36, s3, v104
	s_and_b64 s[14:15], s[74:75], s[8:9]
	v_cmp_gt_i32_e32 vcc, s10, v36
	s_and_b64 s[14:15], s[14:15], vcc
	s_and_saveexec_b64 s[72:73], s[14:15]
	s_cbranch_execz .LBB0_488
	v_mov_b32_e32 v42, v217
	v_fmac_f32_e32 v42, 0x3db504f3, v37
.LBB0_488:
	s_or_b64 exec, exec, s[72:73]
	v_or_b32_e32 v36, s3, v106
	s_and_b64 s[14:15], s[76:77], s[8:9]
	v_cmp_gt_i32_e32 vcc, s10, v36
	s_and_b64 s[14:15], s[14:15], vcc
	v_mov_b32_e32 v36, 0xf149f2ca
	v_mov_b32_e32 v37, 0xf149f2ca
	s_and_saveexec_b64 s[72:73], s[14:15]
	s_cbranch_execz .LBB0_490
	v_mov_b32_e32 v37, v218
	v_fmac_f32_e32 v37, 0x3db504f3, v38
.LBB0_490:
	s_or_b64 exec, exec, s[72:73]
	v_or_b32_e32 v38, s3, v108
	s_and_b64 s[14:15], s[84:85], s[8:9]
	v_cmp_gt_i32_e32 vcc, s10, v38
	s_and_b64 s[14:15], s[14:15], vcc
	s_and_saveexec_b64 s[72:73], s[14:15]
	s_cbranch_execz .LBB0_492
	v_mov_b32_e32 v36, v219
	v_fmac_f32_e32 v36, 0x3db504f3, v39
.LBB0_492:
	s_or_b64 exec, exec, s[72:73]
	v_or_b32_e32 v38, s3, v110
	s_and_b64 s[14:15], s[88:89], s[8:9]
	v_cmp_gt_i32_e32 vcc, s10, v38
	s_and_b64 s[14:15], s[14:15], vcc
	v_mov_b32_e32 v38, 0xf149f2ca
	v_mov_b32_e32 v39, 0xf149f2ca
	s_and_saveexec_b64 s[72:73], s[14:15]
	s_cbranch_execz .LBB0_494
	v_mov_b32_e32 v39, v220
	v_fmac_f32_e32 v39, 0x3db504f3, v32
.LBB0_494:
	s_or_b64 exec, exec, s[72:73]
	v_or_b32_e32 v32, s3, v112
	s_and_b64 s[14:15], s[28:29], s[8:9]
	v_cmp_gt_i32_e32 vcc, s10, v32
	s_and_b64 s[14:15], s[14:15], vcc
	s_and_saveexec_b64 s[72:73], s[14:15]
	s_cbranch_execz .LBB0_496
	v_mov_b32_e32 v38, v221
	v_fmac_f32_e32 v38, 0x3db504f3, v33
.LBB0_496:
	s_or_b64 exec, exec, s[72:73]
	v_or_b32_e32 v32, s3, v114
	s_and_b64 s[14:15], s[30:31], s[8:9]
	v_cmp_gt_i32_e32 vcc, s10, v32
	s_and_b64 s[14:15], s[14:15], vcc
	v_mov_b32_e32 v32, 0xf149f2ca
	v_mov_b32_e32 v33, 0xf149f2ca
	s_and_saveexec_b64 s[72:73], s[14:15]
	s_cbranch_execz .LBB0_498
	v_mov_b32_e32 v33, v222
	v_fmac_f32_e32 v33, 0x3db504f3, v34
.LBB0_498:
	s_or_b64 exec, exec, s[72:73]
	v_or_b32_e32 v34, s3, v116
	s_and_b64 s[8:9], s[34:35], s[8:9]
	v_cmp_gt_i32_e32 vcc, s10, v34
	s_and_b64 s[14:15], s[8:9], vcc
	s_and_saveexec_b64 s[8:9], s[14:15]
	s_cbranch_execz .LBB0_500
	v_mov_b32_e32 v32, v223
	v_fmac_f32_e32 v32, 0x3db504f3, v35

; __device__ __forceinline__ void attnA_item(const Frame& F, const Args& a, int item) {
;     ...
;     for (int ct = 0; ct < 12; ++ct)
; #pragma unroll
;         for (int j = 0; j < 4; ++j) { const int kk = 16 * ct + 4 * fq + j; const int rel = kk - 64 - qq; const int kp = kpw + kk;
;             const bool valid = (rel >= -64) && (rel <= 64) && (kp >= 0) && (kp < L);
;             const float bias = tab[valid ? rel + 64 : 64];
;             const float l = valid ? s[ct][j] * scale + bias : -1e30f; s[ct][j] = l; mx = fmaxf(mx, l); }
.LBB0_502:
	s_or_b64 exec, exec, s[8:9]
	v_add_u32_e32 v20, s3, v119
	v_cmp_gt_i32_e32 vcc, s10, v20
	s_and_saveexec_b64 s[8:9], vcc
	s_cbranch_execz .LBB0_504
	v_mov_b32_e32 v35, v225
	v_fmac_f32_e32 v35, 0x3db504f3, v21
.LBB0_504:
	s_or_b64 exec, exec, s[8:9]
	v_add_u32_e32 v20, s3, v121
	v_cmp_gt_i32_e32 vcc, s10, v20
	v_mov_b32_e32 v20, 0xf149f2ca
	v_mov_b32_e32 v21, 0xf149f2ca
	s_and_saveexec_b64 s[8:9], vcc
	s_cbranch_execz .LBB0_506
	v_mov_b32_e32 v21, v226
	v_fmac_f32_e32 v21, 0x3db504f3, v22
.LBB0_506:
	s_or_b64 exec, exec, s[8:9]
	v_add_u32_e32 v22, s3, v123
	v_cmp_gt_i32_e32 vcc, s10, v22
	s_and_saveexec_b64 s[8:9], vcc
	s_cbranch_execz .LBB0_508
	v_mov_b32_e32 v20, v227
	v_fmac_f32_e32 v20, 0x3db504f3, v23
.LBB0_508:
	s_or_b64 exec, exec, s[8:9]
	v_add_u32_e32 v22, s3, v125
	v_cmp_gt_i32_e32 vcc, s10, v22
	v_mov_b32_e32 v22, 0xf149f2ca
	v_mov_b32_e32 v23, 0xf149f2ca
	s_and_saveexec_b64 s[8:9], vcc
	s_cbranch_execz .LBB0_510
	v_mov_b32_e32 v23, v228
	v_fmac_f32_e32 v23, 0x3db504f3, v16
.LBB0_510:
	s_or_b64 exec, exec, s[8:9]
	v_add_u32_e32 v16, s3, v127
	v_cmp_gt_i32_e32 vcc, s10, v16
	s_and_saveexec_b64 s[8:9], vcc
	s_cbranch_execz .LBB0_512
	v_mov_b32_e32 v22, v229
	v_fmac_f32_e32 v22, 0x3db504f3, v17
.LBB0_512:
	s_or_b64 exec, exec, s[8:9]
	v_add_u32_e32 v16, s3, v129
	v_cmp_gt_i32_e32 vcc, s10, v16
	v_mov_b32_e32 v16, 0xf149f2ca
	v_mov_b32_e32 v17, 0xf149f2ca
	s_and_saveexec_b64 s[8:9], vcc
	s_cbranch_execz .LBB0_514
	v_mov_b32_e32 v17, v230
	v_fmac_f32_e32 v17, 0x3db504f3, v18
.LBB0_514:
	s_or_b64 exec, exec, s[8:9]
	v_add_u32_e32 v18, s3, v131
	v_cmp_gt_i32_e32 vcc, s10, v18
	s_and_saveexec_b64 s[8:9], vcc
	s_cbranch_execz .LBB0_516
	v_mov_b32_e32 v16, v231
	v_fmac_f32_e32 v16, 0x3db504f3, v19
.LBB0_516:
	s_or_b64 exec, exec, s[8:9]
	v_add_u32_e32 v18, s3, v133
	v_cmp_gt_i32_e32 vcc, s10, v18
	v_mov_b32_e32 v18, 0xf149f2ca
	v_mov_b32_e32 v19, 0xf149f2ca
	s_and_saveexec_b64 s[8:9], vcc
	s_cbranch_execz .LBB0_518
	v_mov_b32_e32 v19, v232
	v_fmac_f32_e32 v19, 0x3db504f3, v28
.LBB0_518:
	s_or_b64 exec, exec, s[8:9]
	v_add_u32_e32 v28, s3, v135
	v_cmp_gt_i32_e32 vcc, s10, v28
	s_and_saveexec_b64 s[8:9], vcc
	s_cbranch_execz .LBB0_520
	v_mov_b32_e32 v18, v233
	v_fmac_f32_e32 v18, 0x3db504f3, v29
.LBB0_520:
	s_or_b64 exec, exec, s[8:9]
	v_add_u32_e32 v28, s3, v137
	v_cmp_gt_i32_e32 vcc, s10, v28
	v_mov_b32_e32 v28, 0xf149f2ca
	v_mov_b32_e32 v29, 0xf149f2ca
	s_and_saveexec_b64 s[8:9], vcc
	s_cbranch_execz .LBB0_522
	v_mov_b32_e32 v29, v234
	v_fmac_f32_e32 v29, 0x3db504f3, v30
.LBB0_522:
	s_or_b64 exec, exec, s[8:9]
	v_add_u32_e32 v30, s3, v139
	v_cmp_gt_i32_e32 vcc, s10, v30
	s_and_saveexec_b64 s[8:9], vcc
	s_cbranch_execz .LBB0_524
	v_mov_b32_e32 v28, v235
	v_fmac_f32_e32 v28, 0x3db504f3, v31
.LBB0_524:
	s_or_b64 exec, exec, s[8:9]
	v_add_u32_e32 v30, s3, v141
	v_cmp_gt_i32_e32 vcc, s10, v30
	v_mov_b32_e32 v30, 0xf149f2ca
	v_mov_b32_e32 v31, 0xf149f2ca
	s_and_saveexec_b64 s[8:9], vcc
	s_cbranch_execz .LBB0_526
	v_mov_b32_e32 v31, v236
	v_fmac_f32_e32 v31, 0x3db504f3, v24
.LBB0_526:
	s_or_b64 exec, exec, s[8:9]
	v_add_u32_e32 v24, s3, v143
	v_cmp_gt_i32_e32 vcc, s10, v24
	s_and_saveexec_b64 s[8:9], vcc
	s_cbranch_execz .LBB0_528
	v_mov_b32_e32 v30, v237
	v_fmac_f32_e32 v30, 0x3db504f3, v25
.LBB0_528:
	s_or_b64 exec, exec, s[8:9]
	v_add_u32_e32 v24, s3, v146
	v_cmp_gt_i32_e32 vcc, s10, v24
	v_mov_b32_e32 v24, 0xf149f2ca
	v_mov_b32_e32 v25, 0xf149f2ca
	s_and_saveexec_b64 s[8:9], vcc
	s_cbranch_execz .LBB0_530
	v_mov_b32_e32 v25, v238
	v_fmac_f32_e32 v25, 0x3db504f3, v26
.LBB0_530:
	s_or_b64 exec, exec, s[8:9]
	v_add_u32_e32 v26, s3, v148
	v_cmp_gt_i32_e32 vcc, s10, v26
	s_and_saveexec_b64 s[8:9], vcc
	s_cbranch_execz .LBB0_532
	v_mov_b32_e32 v24, v239
	v_fmac_f32_e32 v24, 0x3db504f3, v27
; __device__ __forceinline__ void attnA_item(const Frame& F, const Args& a, int item) {
;     ...
;     for (int ct = 0; ct < 12; ++ct)
; #pragma unroll
;         for (int j = 0; j < 4; ++j) { const int kk = 16 * ct + 4 * fq + j; const int rel = kk - 64 - qq; const int kp = kpw + kk;
;             const bool valid = (rel >= -64) && (rel <= 64) && (kp >= 0) && (kp < L);
;             const float bias = tab[valid ? rel + 64 : 64];
;             const float l = valid ? s[ct][j] * scale + bias : -1e30f; s[ct][j] = l; mx = fmaxf(mx, l); }
.LBB0_532:
	s_or_b64 exec, exec, s[8:9]
	v_add_u32_e32 v26, s3, v150
	v_cmp_gt_i32_e32 vcc, s10, v26
	s_and_b64 s[12:13], s[36:37], vcc
	v_mov_b32_e32 v26, 0xf149f2ca
	v_mov_b32_e32 v27, 0xf149f2ca
	s_and_saveexec_b64 s[8:9], s[12:13]
	s_cbranch_execz .LBB0_534
	v_mov_b32_e32 v27, v240
	v_fmac_f32_e32 v27, 0x3db504f3, v12
.LBB0_534:
	s_or_b64 exec, exec, s[8:9]
	v_add_u32_e32 v12, s3, v152
	v_cmp_gt_i32_e32 vcc, s10, v12
	s_and_b64 s[12:13], s[38:39], vcc
	s_and_saveexec_b64 s[8:9], s[12:13]
	s_cbranch_execz .LBB0_536
	v_mov_b32_e32 v26, v241
	v_fmac_f32_e32 v26, 0x3db504f3, v13
.LBB0_536:
	s_or_b64 exec, exec, s[8:9]
	v_add_u32_e32 v12, s3, v154
	v_cmp_gt_i32_e32 vcc, s10, v12
	s_and_b64 s[12:13], s[40:41], vcc
	v_mov_b32_e32 v12, 0xf149f2ca
	v_mov_b32_e32 v13, 0xf149f2ca
	s_and_saveexec_b64 s[8:9], s[12:13]
	s_cbranch_execz .LBB0_538
	v_mov_b32_e32 v13, v244
	v_fmac_f32_e32 v13, 0x3db504f3, v14
.LBB0_538:
	s_or_b64 exec, exec, s[8:9]
	v_add_u32_e32 v14, s3, v156
	v_cmp_gt_i32_e32 vcc, s10, v14
	s_and_b64 s[12:13], s[42:43], vcc
	s_and_saveexec_b64 s[8:9], s[12:13]
	s_cbranch_execz .LBB0_540
	v_mov_b32_e32 v12, v245
	v_fmac_f32_e32 v12, 0x3db504f3, v15
.LBB0_540:
	s_or_b64 exec, exec, s[8:9]
	v_add_u32_e32 v14, s3, v158
	v_cmp_gt_i32_e32 vcc, s10, v14
	s_and_b64 s[12:13], s[44:45], vcc
	v_mov_b32_e32 v14, 0xf149f2ca
	v_mov_b32_e32 v15, 0xf149f2ca
	s_and_saveexec_b64 s[8:9], s[12:13]
	s_cbranch_execz .LBB0_542
	v_mov_b32_e32 v15, v246
	v_fmac_f32_e32 v15, 0x3db504f3, v8
.LBB0_542:
	s_or_b64 exec, exec, s[8:9]
	v_add_u32_e32 v8, s3, v160
	v_cmp_gt_i32_e32 vcc, s10, v8
	s_and_b64 s[12:13], s[46:47], vcc
	s_and_saveexec_b64 s[8:9], s[12:13]
	s_cbranch_execz .LBB0_544
	v_mov_b32_e32 v14, v247
	v_fmac_f32_e32 v14, 0x3db504f3, v9
.LBB0_544:
	s_or_b64 exec, exec, s[8:9]
	v_add_u32_e32 v8, s3, v162
	v_cmp_gt_i32_e32 vcc, s10, v8
	s_and_b64 s[12:13], s[48:49], vcc
	v_mov_b32_e32 v8, 0xf149f2ca
	v_mov_b32_e32 v9, 0xf149f2ca
	s_and_saveexec_b64 s[8:9], s[12:13]
	s_cbranch_execz .LBB0_546
	v_mov_b32_e32 v9, v248
	v_fmac_f32_e32 v9, 0x3db504f3, v10
.LBB0_546:
	s_or_b64 exec, exec, s[8:9]
	v_add_u32_e32 v10, s3, v164
	v_cmp_gt_i32_e32 vcc, s10, v10
	s_and_b64 s[12:13], s[50:51], vcc
	s_and_saveexec_b64 s[8:9], s[12:13]
	s_cbranch_execz .LBB0_548
	v_mov_b32_e32 v8, v249
	v_fmac_f32_e32 v8, 0x3db504f3, v11
.LBB0_548:
	s_or_b64 exec, exec, s[8:9]
	v_add_u32_e32 v10, s3, v166
	v_cmp_gt_i32_e32 vcc, s10, v10
	s_and_b64 s[12:13], s[52:53], vcc
	v_mov_b32_e32 v10, 0xf149f2ca
	v_mov_b32_e32 v11, 0xf149f2ca
	s_and_saveexec_b64 s[8:9], s[12:13]
	s_cbranch_execz .LBB0_550
	v_mov_b32_e32 v11, v250
	v_fmac_f32_e32 v11, 0x3db504f3, v4
.LBB0_550:
	s_or_b64 exec, exec, s[8:9]
	v_add_u32_e32 v4, s3, v168
	v_cmp_gt_i32_e32 vcc, s10, v4
	s_and_b64 s[12:13], s[54:55], vcc
	s_and_saveexec_b64 s[8:9], s[12:13]
	s_cbranch_execz .LBB0_552
	v_mov_b32_e32 v10, v251
	v_fmac_f32_e32 v10, 0x3db504f3, v5
.LBB0_552:
	s_or_b64 exec, exec, s[8:9]
	v_add_u32_e32 v4, s3, v170
	v_cmp_gt_i32_e32 vcc, s10, v4
	s_and_b64 s[12:13], s[56:57], vcc
	v_mov_b32_e32 v4, 0xf149f2ca
	v_mov_b32_e32 v5, 0xf149f2ca
	s_and_saveexec_b64 s[8:9], s[12:13]
	s_cbranch_execz .LBB0_554
	v_mov_b32_e32 v5, v252
	v_fmac_f32_e32 v5, 0x3db504f3, v6
.LBB0_554:
	s_or_b64 exec, exec, s[8:9]
	v_add_u32_e32 v6, s3, v172
	v_cmp_gt_i32_e32 vcc, s10, v6
	s_and_b64 s[12:13], s[58:59], vcc
	s_and_saveexec_b64 s[8:9], s[12:13]
	s_cbranch_execz .LBB0_556
	v_mov_b32_e32 v4, v253
	v_fmac_f32_e32 v4, 0x3db504f3, v7
.LBB0_556:
	s_or_b64 exec, exec, s[8:9]
	v_add_u32_e32 v6, s3, v174
	v_cmp_gt_i32_e32 vcc, s10, v6
	s_and_b64 s[12:13], s[60:61], vcc
	v_mov_b32_e32 v6, 0xf149f2ca
	v_mov_b32_e32 v7, 0xf149f2ca
	s_and_saveexec_b64 s[8:9], s[12:13]
	s_cbranch_execz .LBB0_558
	v_mov_b32_e32 v7, v254
	v_fmac_f32_e32 v7, 0x3db504f3, v0
.LBB0_558:
	s_or_b64 exec, exec, s[8:9]
	v_add_u32_e32 v0, s3, v176
	v_cmp_gt_i32_e32 vcc, s10, v0
	s_and_b64 s[12:13], s[62:63], vcc
	s_and_saveexec_b64 s[8:9], s[12:13]
	s_cbranch_execz .LBB0_560
	v_mov_b32_e32 v6, v255
	v_fmac_f32_e32 v6, 0x3db504f3, v1
